# code placement pin: .p2align 6 on the GEMM1, branch and out GEMM main-loop heads (back-edge targets on 64-byte boundaries), on top of v37
# speedup vs baseline: 1.0063x; 1.0063x over previous
;     __device__ bool next(int i, Unit& u) const { if (i != 0) return false; u.pm = pm; u.pn = pn; return true; }
;     __device__ bool next(int i, Unit& u) const { const int L = i * G + c; if (L >= 256) return false; u.pm = L; u.pn = L >> 6; return true; }
;     __device__ bool next(int i, Unit& u) const { Unit t; if (!so.next(i >> 2, t)) return false; const int b = i & 3; u.pm = b * 64 + t.pm; u.pn = b * 8 + t.pn; return true; }
; template <bool ALIGN_EPI, bool SP2, class Epi, class Sched>
; __device__ __forceinline__ void gemm_phase(LAS unsigned char* lds, const Gemm g, const Sched& S, const Epi& E) {
;     ...
;     f32x4 acc[2][2][4][2];
; #pragma unroll
;     for (int a = 0; a < 2; ++a)
; #pragma unroll
;         for (int b = 0; b < 2; ++b)
; #pragma unroll
;             for (int m = 0; m < 4; ++m)
; #pragma unroll
;                 for (int n = 0; n < 2; ++n) acc[a][b][m][n] = (f32x4){0.f, 0.f, 0.f, 0.f};
;     ...
;     for (;;) {
;         const bool has_next = S.next(ui + 1, nxt);
;         const char* nA = has_next ? (const char*)g.A + (size_t)nxt.pm * tstep : cA; const char* nB = has_next ? (const char*)g.Bt + (size_t)nxt.pn * tstep : cB;
;         for (int t = 0; t < nt; t += 2) {
.LBB0_233:
	v_mov_b32_e32 v117, 0
	s_andn2_b64 vcc, exec, s[38:39]
	v_mov_b32_e32 v116, v117
	v_mov_b32_e32 v115, v117
	v_mov_b32_e32 v114, v117
	v_mov_b32_e32 v129, v117
	v_mov_b32_e32 v128, v117
	v_mov_b32_e32 v127, v117
	v_mov_b32_e32 v126, v117
	v_mov_b32_e32 v101, v117
	v_mov_b32_e32 v100, v117
	v_mov_b32_e32 v99, v117
	v_mov_b32_e32 v98, v117
	v_mov_b32_e32 v113, v117
	v_mov_b32_e32 v112, v117
	v_mov_b32_e32 v111, v117
	v_mov_b32_e32 v110, v117
	v_mov_b32_e32 v85, v117
	v_mov_b32_e32 v84, v117
	v_mov_b32_e32 v83, v117
	v_mov_b32_e32 v82, v117
	v_mov_b32_e32 v97, v117
	v_mov_b32_e32 v96, v117
	v_mov_b32_e32 v95, v117
	v_mov_b32_e32 v94, v117
	v_mov_b32_e32 v69, v117
	v_mov_b32_e32 v68, v117
	v_mov_b32_e32 v67, v117
	v_mov_b32_e32 v66, v117
	v_mov_b32_e32 v81, v117
	v_mov_b32_e32 v80, v117
	v_mov_b32_e32 v79, v117
	v_mov_b32_e32 v78, v117
	v_mov_b32_e32 v125, v117
	v_mov_b32_e32 v124, v117
	v_mov_b32_e32 v123, v117
	v_mov_b32_e32 v122, v117
	v_mov_b32_e32 v121, v117
	v_mov_b32_e32 v120, v117
	v_mov_b32_e32 v119, v117
	v_mov_b32_e32 v118, v117
	v_mov_b32_e32 v109, v117
	v_mov_b32_e32 v108, v117
	v_mov_b32_e32 v107, v117
	v_mov_b32_e32 v106, v117
	v_mov_b32_e32 v105, v117
	v_mov_b32_e32 v104, v117
	v_mov_b32_e32 v103, v117
	v_mov_b32_e32 v102, v117
	v_mov_b32_e32 v93, v117
	v_mov_b32_e32 v92, v117
	v_mov_b32_e32 v91, v117
	v_mov_b32_e32 v90, v117
	v_mov_b32_e32 v89, v117
	v_mov_b32_e32 v88, v117
	v_mov_b32_e32 v87, v117
	v_mov_b32_e32 v86, v117
	v_mov_b32_e32 v77, v117
	v_mov_b32_e32 v76, v117
	v_mov_b32_e32 v75, v117
	v_mov_b32_e32 v74, v117
	v_mov_b32_e32 v73, v117
	v_mov_b32_e32 v72, v117
	v_mov_b32_e32 v71, v117
	v_mov_b32_e32 v70, v117
	v_mov_b32_e32 v53, v117
	v_mov_b32_e32 v52, v117
	v_mov_b32_e32 v51, v117
	v_mov_b32_e32 v50, v117
	v_mov_b32_e32 v65, v117
	v_mov_b32_e32 v64, v117
	v_mov_b32_e32 v63, v117
	v_mov_b32_e32 v62, v117
	v_mov_b32_e32 v37, v117
	v_mov_b32_e32 v36, v117
	v_mov_b32_e32 v35, v117
	v_mov_b32_e32 v34, v117
	v_mov_b32_e32 v49, v117
	v_mov_b32_e32 v48, v117
	v_mov_b32_e32 v47, v117
	v_mov_b32_e32 v46, v117
	v_mov_b32_e32 v21, v117
	v_mov_b32_e32 v20, v117
	v_mov_b32_e32 v19, v117
	v_mov_b32_e32 v18, v117
	v_mov_b32_e32 v33, v117
	v_mov_b32_e32 v32, v117
	v_mov_b32_e32 v31, v117
	v_mov_b32_e32 v30, v117
	v_mov_b32_e32 v5, v117
	v_mov_b32_e32 v4, v117
	v_mov_b32_e32 v3, v117
	v_mov_b32_e32 v2, v117
	v_mov_b32_e32 v17, v117
	v_mov_b32_e32 v16, v117
	v_mov_b32_e32 v15, v117
	v_mov_b32_e32 v14, v117
	v_mov_b32_e32 v61, v117
	v_mov_b32_e32 v60, v117
	v_mov_b32_e32 v59, v117
	v_mov_b32_e32 v58, v117
	v_mov_b32_e32 v57, v117
	v_mov_b32_e32 v56, v117
	v_mov_b32_e32 v55, v117
	v_mov_b32_e32 v54, v117
	v_mov_b32_e32 v45, v117
	v_mov_b32_e32 v44, v117
	v_mov_b32_e32 v43, v117
	v_mov_b32_e32 v42, v117
	v_mov_b32_e32 v41, v117
	v_mov_b32_e32 v40, v117
	v_mov_b32_e32 v39, v117
	v_mov_b32_e32 v38, v117
	v_mov_b32_e32 v29, v117
	v_mov_b32_e32 v28, v117
	v_mov_b32_e32 v27, v117
	v_mov_b32_e32 v26, v117
	v_mov_b32_e32 v25, v117
	v_mov_b32_e32 v24, v117
	v_mov_b32_e32 v23, v117
	v_mov_b32_e32 v22, v117
	v_mov_b32_e32 v13, v117
	v_mov_b32_e32 v12, v117
	v_mov_b32_e32 v11, v117
	v_mov_b32_e32 v10, v117
	v_mov_b32_e32 v9, v117
	v_mov_b32_e32 v8, v117
	v_mov_b32_e32 v7, v117
	v_mov_b32_e32 v6, v117
	s_cbranch_vccnz .LBB0_236
	s_add_u32 s42, s90, 0x80
	s_addc_u32 s43, s91, 0
	s_add_u32 s24, s44, 0x100
	v_mov_b32_e32 v6, 0
	s_addc_u32 s71, s45, 0
	s_mov_b32 s44, 0
	.p2align 6

;     __device__ bool next(int i, Unit& u) const { if (i != 0) return false; u.pm = pm; u.pn = pn; return true; }
;     __device__ bool next(int i, Unit& u) const { const int L = i * G + c; if (L >= 256) return false; u.pm = L; u.pn = L >> 6; return true; }
;     __device__ bool next(int i, Unit& u) const { Unit t; if (!so.next(i >> 2, t)) return false; const int b = i & 3; u.pm = b * 64 + t.pm; u.pn = b * 8 + t.pn; return true; }
; template <bool ALIGN_EPI, bool SP2, class Epi, class Sched>
; __device__ __forceinline__ void gemm_phase(LAS unsigned char* lds, const Gemm g, const Sched& S, const Epi& E) {
;     ...
;     for (;;) {
;         const bool has_next = S.next(ui + 1, nxt);
;         const char* nA = has_next ? (const char*)g.A + (size_t)nxt.pm * tstep : cA; const char* nB = has_next ? (const char*)g.Bt + (size_t)nxt.pn * tstep : cB;
;         for (int t = 0; t < nt; t += 2) {
;             const bool last = (t == nt - 2);
;             const char* a1 = cA + (size_t)(t + 1) * kstep;
;             const char* a2 = last ? nA : cA + (size_t)(t + 2) * kstep; const char* b2 = last ? nB : cB + (size_t)(t + 2) * kstep;
;             const char* a3 = a2 + kstep; const char* b3 = b2 + kstep;
.LBB0_703:
	s_add_u32 s44, s94, 0x80
	s_addc_u32 s45, s95, 0
	s_add_u32 s92, s92, 0x100
	s_addc_u32 s93, s93, 0
	s_mov_b32 s88, 0
	.p2align 6

;     __device__ bool next(int i, Unit& u) const { if (i != 0) return false; u.pm = pm; u.pn = pn; return true; }
;     __device__ bool next(int i, Unit& u) const { const int L = i * G + c; if (L >= 256) return false; u.pm = L; u.pn = L >> 6; return true; }
;     __device__ bool next(int i, Unit& u) const { Unit t; if (!so.next(i >> 2, t)) return false; const int b = i & 3; u.pm = b * 64 + t.pm; u.pn = b * 8 + t.pn; return true; }
;     __device__ __forceinline__ bool zero_after(const Unit& u) const { return (u.pm >> 6) == 3; }
; template <bool ALIGN_EPI, bool SP2, class Epi, class Sched>
; __device__ __forceinline__ void gemm_phase(LAS unsigned char* lds, const Gemm g, const Sched& S, const Epi& E) {
;     ...
;     for (;;) {
;         const bool has_next = S.next(ui + 1, nxt);
;         const char* nA = has_next ? (const char*)g.A + (size_t)nxt.pm * tstep : cA; const char* nB = has_next ? (const char*)g.Bt + (size_t)nxt.pn * tstep : cB;
;         for (int t = 0; t < nt; t += 2) {
;     ...
;         if (E.zero_after(cur))
; #pragma unroll
;         for (int a = 0; a < 2; ++a)
; #pragma unroll
;             for (int b = 0; b < 2; ++b)
; #pragma unroll
;                 for (int m = 0; m < 4; ++m)
; #pragma unroll
;                     for (int n = 0; n < 2; ++n) acc[a][b][m][n] = (f32x4){0.f, 0.f, 0.f, 0.f};
;         cur = nxt; cA = nA; cB = nB; ++ui;
.LBB0_833:
	v_mov_b32_e32 v129, 0
	s_andn2_b64 vcc, exec, s[44:45]
	v_mov_b32_e32 v128, v129
	v_mov_b32_e32 v127, v129
	v_mov_b32_e32 v126, v129
	v_mov_b32_e32 v125, v129
	v_mov_b32_e32 v124, v129
	v_mov_b32_e32 v123, v129
	v_mov_b32_e32 v122, v129
	v_mov_b32_e32 v113, v129
	v_mov_b32_e32 v112, v129
	v_mov_b32_e32 v111, v129
	v_mov_b32_e32 v110, v129
	v_mov_b32_e32 v109, v129
	v_mov_b32_e32 v108, v129
	v_mov_b32_e32 v107, v129
	v_mov_b32_e32 v106, v129
	v_mov_b32_e32 v97, v129
	v_mov_b32_e32 v96, v129
	v_mov_b32_e32 v95, v129
	v_mov_b32_e32 v94, v129
	v_mov_b32_e32 v93, v129
	v_mov_b32_e32 v92, v129
	v_mov_b32_e32 v91, v129
	v_mov_b32_e32 v90, v129
	v_mov_b32_e32 v81, v129
	v_mov_b32_e32 v80, v129
	v_mov_b32_e32 v79, v129
	v_mov_b32_e32 v78, v129
	v_mov_b32_e32 v77, v129
	v_mov_b32_e32 v76, v129
	v_mov_b32_e32 v75, v129
	v_mov_b32_e32 v74, v129
	v_mov_b32_e32 v121, v129
	v_mov_b32_e32 v120, v129
	v_mov_b32_e32 v119, v129
	v_mov_b32_e32 v118, v129
	v_mov_b32_e32 v117, v129
	v_mov_b32_e32 v116, v129
	v_mov_b32_e32 v115, v129
	v_mov_b32_e32 v114, v129
	v_mov_b32_e32 v105, v129
	v_mov_b32_e32 v104, v129
	v_mov_b32_e32 v103, v129
	v_mov_b32_e32 v102, v129
	v_mov_b32_e32 v101, v129
	v_mov_b32_e32 v100, v129
	v_mov_b32_e32 v99, v129
	v_mov_b32_e32 v98, v129
	v_mov_b32_e32 v89, v129
	v_mov_b32_e32 v88, v129
	v_mov_b32_e32 v87, v129
	v_mov_b32_e32 v86, v129
	v_mov_b32_e32 v85, v129
	v_mov_b32_e32 v84, v129
	v_mov_b32_e32 v83, v129
	v_mov_b32_e32 v82, v129
	v_mov_b32_e32 v73, v129
	v_mov_b32_e32 v72, v129
	v_mov_b32_e32 v71, v129
	v_mov_b32_e32 v70, v129
	v_mov_b32_e32 v69, v129
	v_mov_b32_e32 v68, v129
	v_mov_b32_e32 v67, v129
	v_mov_b32_e32 v66, v129
	v_mov_b32_e32 v65, v129
	v_mov_b32_e32 v64, v129
	v_mov_b32_e32 v63, v129
	v_mov_b32_e32 v62, v129
	v_mov_b32_e32 v61, v129
	v_mov_b32_e32 v60, v129
	v_mov_b32_e32 v59, v129
	v_mov_b32_e32 v58, v129
	v_mov_b32_e32 v49, v129
	v_mov_b32_e32 v48, v129
	v_mov_b32_e32 v47, v129
	v_mov_b32_e32 v46, v129
	v_mov_b32_e32 v45, v129
	v_mov_b32_e32 v44, v129
	v_mov_b32_e32 v43, v129
	v_mov_b32_e32 v42, v129
	v_mov_b32_e32 v33, v129
	v_mov_b32_e32 v32, v129
	v_mov_b32_e32 v31, v129
	v_mov_b32_e32 v30, v129
	v_mov_b32_e32 v29, v129
	v_mov_b32_e32 v28, v129
	v_mov_b32_e32 v27, v129
	v_mov_b32_e32 v26, v129
	v_mov_b32_e32 v17, v129
	v_mov_b32_e32 v16, v129
	v_mov_b32_e32 v15, v129
	v_mov_b32_e32 v14, v129
	v_mov_b32_e32 v13, v129
	v_mov_b32_e32 v12, v129
	v_mov_b32_e32 v11, v129
	v_mov_b32_e32 v10, v129
	v_mov_b32_e32 v57, v129
	v_mov_b32_e32 v56, v129
	v_mov_b32_e32 v55, v129
	v_mov_b32_e32 v54, v129
	v_mov_b32_e32 v53, v129
	v_mov_b32_e32 v52, v129
	v_mov_b32_e32 v51, v129
	v_mov_b32_e32 v50, v129
	v_mov_b32_e32 v41, v129
	v_mov_b32_e32 v40, v129
	v_mov_b32_e32 v39, v129
	v_mov_b32_e32 v38, v129
	v_mov_b32_e32 v37, v129
	v_mov_b32_e32 v36, v129
	v_mov_b32_e32 v35, v129
	v_mov_b32_e32 v34, v129
	v_mov_b32_e32 v25, v129
	v_mov_b32_e32 v24, v129
	v_mov_b32_e32 v23, v129
	v_mov_b32_e32 v22, v129
	v_mov_b32_e32 v21, v129
	v_mov_b32_e32 v20, v129
	v_mov_b32_e32 v19, v129
	v_mov_b32_e32 v18, v129
	v_mov_b32_e32 v9, v129
	v_mov_b32_e32 v8, v129
	v_mov_b32_e32 v7, v129
	v_mov_b32_e32 v6, v129
	v_mov_b32_e32 v5, v129
	v_mov_b32_e32 v4, v129
	v_mov_b32_e32 v3, v129
	v_mov_b32_e32 v2, v129
	s_cbranch_vccnz .LBB0_836
	s_add_u32 s86, s86, 0x80
	s_addc_u32 s87, s87, 0
	s_add_u32 s24, s90, 0x100
	v_mov_b32_e32 v2, 0
	s_addc_u32 s90, s91, 0
	s_mov_b32 s88, 0
	.p2align 6
